# out-proj AB: rows 16384+ as 32x32 K-split tail blocks (2 tile rounds instead of 3); dn_prep items 1024..1031 moved to 8 light SWA-side WGs at phase-3 start with completion counter awaited by the level
# speedup vs baseline: 1.6702x; 1.0161x over previous
_Z14fwd_megakernel6Params:
	s_mov_b32 s78, s2
	s_mov_b32 s98, 0
	s_load_dwordx2 s[2:3], s[0:1], 0xc0
	s_add_u32 s8, s0, 0xd0
	s_addc_u32 s9, s1, 0
	v_and_b32_e32 v218, 0x3ff, v0
	v_cmp_eq_u32_e64 s[4:5], 0, v218
	s_waitcnt lgkmcnt(0)
	v_writelane_b32 v252, s2, 0
	s_nop 1
	v_writelane_b32 v252, s3, 1
	s_load_dword s38, s[0:1], 0xd8
	s_load_dwordx2 s[2:3], s[0:1], 0xd0
	s_waitcnt lgkmcnt(0)
	v_writelane_b32 v252, s2, 2
	s_nop 1
	v_writelane_b32 v252, s3, 3
	s_mov_b64 s[2:3], exec
	v_writelane_b32 v252, s4, 4
	s_nop 1
	v_writelane_b32 v252, s5, 5
	s_and_b64 s[4:5], s[2:3], s[4:5]
	s_mov_b64 exec, s[4:5]
	s_cbranch_execz .LBB0_2
	v_mov_b32_e32 v2, 0
	v_mov_b32_e32 v3, v2
	v_mov_b32_e32 v4, v2
	v_mov_b32_e32 v5, v2
	v_mov_b32_e32 v1, 0x12400
	ds_write_b128 v1, v[2:5]

.LBB0_205:
	s_or_b64 exec, exec, s[0:1]
	v_lshlrev_b32_e32 v4, 1, v0
	v_mad_u32_u24 v69, v36, s34, v4
	s_waitcnt lgkmcnt(0)
	s_barrier
	ds_read_b128 v[0:3], v69 offset:17408
	v_or_b32_e32 v35, v34, v36
	v_mad_u64_u32 v[32:33], s[0:1], v35, s34, v[4:5]
	ds_read_b128 v[38:41], v32 offset:53248
	ds_read_b128 v[42:45], v69 offset:17440
	ds_read_b128 v[88:91], v32 offset:53280
	ds_read_b128 v[92:95], v32 offset:34816
	ds_read_b128 v[96:99], v32 offset:34848
	s_waitcnt lgkmcnt(4)
	v_mfma_f32_32x32x16_bf16 v[16:31], v[0:3], v[38:41], 0
	ds_read_b128 v[46:49], v69 offset:17472
	ds_read_b128 v[100:103], v32 offset:53312
	s_lshl_b64 s[0:1], s[4:5], 1
	v_readlane_b32 s4, v250, 5
	s_add_u32 s4, s4, s0
	v_readlane_b32 s5, v250, 7
	v_lshlrev_b32_e32 v50, 6, v35
	s_waitcnt lgkmcnt(3)
	v_mfma_f32_32x32x16_bf16 v[0:15], v[92:95], v[0:3], 0
	s_addc_u32 s5, s5, s1
	v_ashrrev_i32_e32 v51, 31, v50
	v_lshl_add_u64 v[50:51], v[50:51], 1, s[4:5]
	v_lshlrev_b32_e32 v64, 1, v37
	s_add_u32 s0, s56, s0
	v_lshl_add_u64 v[70:71], v[50:51], 0, v[64:65]
	s_addc_u32 s1, s57, s1
	v_mfma_f32_32x32x16_bf16 v[16:31], v[42:45], v[88:91], v[16:31]
	v_ashrrev_i32_e32 v35, 31, v34
	v_lshl_add_u64 v[34:35], v[34:35], 1, s[0:1]
	v_lshl_add_u64 v[116:117], v[34:35], 0, v[64:65]
	v_lshlrev_b32_e32 v64, 8, v36
	v_lshl_add_u64 v[118:119], v[116:117], 0, v[64:65]
	v_or_b32_e32 v64, 0x2000, v64
	v_readlane_b32 s0, v252, 2
	s_waitcnt lgkmcnt(2)
	v_mfma_f32_32x32x16_bf16 v[0:15], v[96:99], v[42:45], v[0:15]
	ds_read_b128 v[42:45], v69 offset:17504
	ds_read_b128 v[104:107], v32 offset:53344
	ds_read_b128 v[108:111], v32 offset:34880
	ds_read_b128 v[112:115], v32 offset:34912
	s_add_i32 s80, s80, s0
	s_add_u32 s2, s2, s40
	s_addc_u32 s3, s3, s41
	s_cmpk_gt_i32 s80, 0x3ff
	s_waitcnt lgkmcnt(4)
	v_mfma_f32_32x32x16_bf16 v[16:31], v[46:49], v[100:103], v[16:31]
	v_readlane_b32 s1, v252, 3
	s_waitcnt lgkmcnt(1)
	v_mfma_f32_32x32x16_bf16 v[0:15], v[108:111], v[46:49], v[0:15]
	v_mfma_f32_32x32x16_bf16 v[16:31], v[42:45], v[104:107], v[16:31]
	s_waitcnt lgkmcnt(0)
	v_mfma_f32_32x32x16_bf16 v[0:15], v[112:115], v[42:45], v[0:15]
	s_nop 9
	v_and_b32_sdwa v32, v17, v87 dst_sel:DWORD dst_unused:UNUSED_PAD src0_sel:WORD_1 src1_sel:DWORD
	v_and_b32_sdwa v33, v16, v87 dst_sel:DWORD dst_unused:UNUSED_PAD src0_sel:WORD_1 src1_sel:DWORD
	v_add3_u32 v16, v16, v33, s91
	v_add3_u32 v32, v17, v32, s91
	v_and_b32_sdwa v17, v19, v87 dst_sel:DWORD dst_unused:UNUSED_PAD src0_sel:WORD_1 src1_sel:DWORD
	v_and_b32_sdwa v33, v18, v87 dst_sel:DWORD dst_unused:UNUSED_PAD src0_sel:WORD_1 src1_sel:DWORD
	v_add3_u32 v18, v18, v33, s91
	v_add3_u32 v17, v19, v17, s91
	v_perm_b32 v17, v17, v18, s93
	v_perm_b32 v16, v32, v16, s93
	global_store_dwordx2 v[70:71], v[16:17], off
	v_and_b32_sdwa v16, v1, v87 dst_sel:DWORD dst_unused:UNUSED_PAD src0_sel:WORD_1 src1_sel:DWORD
	v_and_b32_sdwa v17, v0, v87 dst_sel:DWORD dst_unused:UNUSED_PAD src0_sel:WORD_1 src1_sel:DWORD
	v_add3_u32 v0, v0, v17, s91
	v_add3_u32 v16, v1, v16, s91
	v_and_b32_sdwa v1, v3, v87 dst_sel:DWORD dst_unused:UNUSED_PAD src0_sel:WORD_1 src1_sel:DWORD
	v_and_b32_sdwa v17, v2, v87 dst_sel:DWORD dst_unused:UNUSED_PAD src0_sel:WORD_1 src1_sel:DWORD
	v_add3_u32 v2, v2, v17, s91
	v_add3_u32 v1, v3, v1, s91
	v_perm_b32 v1, v1, v2, s93
	v_perm_b32 v0, v16, v0, s93
	global_store_dwordx2 v[118:119], v[0:1], off
	v_and_b32_sdwa v1, v20, v87 dst_sel:DWORD dst_unused:UNUSED_PAD src0_sel:WORD_1 src1_sel:DWORD
	v_and_b32_sdwa v0, v21, v87 dst_sel:DWORD dst_unused:UNUSED_PAD src0_sel:WORD_1 src1_sel:DWORD
	v_add3_u32 v2, v20, v1, s91
	v_and_b32_sdwa v1, v23, v87 dst_sel:DWORD dst_unused:UNUSED_PAD src0_sel:WORD_1 src1_sel:DWORD
	v_and_b32_sdwa v3, v22, v87 dst_sel:DWORD dst_unused:UNUSED_PAD src0_sel:WORD_1 src1_sel:DWORD
	v_add3_u32 v0, v21, v0, s91
	v_add3_u32 v3, v22, v3, s91
	v_add3_u32 v1, v23, v1, s91
	v_perm_b32 v1, v1, v3, s93
	v_perm_b32 v0, v0, v2, s93
	global_store_dwordx2 v[70:71], v[0:1], off offset:16
	ds_read_b128 v[0:3], v69 offset:22016
	v_and_b32_sdwa v16, v5, v87 dst_sel:DWORD dst_unused:UNUSED_PAD src0_sel:WORD_1 src1_sel:DWORD
	v_and_b32_sdwa v17, v4, v87 dst_sel:DWORD dst_unused:UNUSED_PAD src0_sel:WORD_1 src1_sel:DWORD
	v_add3_u32 v18, v4, v17, s91
	v_add3_u32 v16, v5, v16, s91
	v_and_b32_sdwa v4, v7, v87 dst_sel:DWORD dst_unused:UNUSED_PAD src0_sel:WORD_1 src1_sel:DWORD
	v_and_b32_sdwa v5, v6, v87 dst_sel:DWORD dst_unused:UNUSED_PAD src0_sel:WORD_1 src1_sel:DWORD
	v_add3_u32 v17, v6, v5, s91
	v_add3_u32 v19, v7, v4, s91
	ds_read_b128 v[4:7], v69 offset:22048
	s_waitcnt lgkmcnt(1)
	v_mfma_f32_32x32x16_bf16 v[48:63], v[0:3], v[38:41], 0
	v_perm_b32 v17, v19, v17, s93
	v_perm_b32 v16, v16, v18, s93
	global_store_dwordx2 v[118:119], v[16:17], off offset:16
	v_and_b32_sdwa v16, v25, v87 dst_sel:DWORD dst_unused:UNUSED_PAD src0_sel:WORD_1 src1_sel:DWORD
	v_and_b32_sdwa v17, v24, v87 dst_sel:DWORD dst_unused:UNUSED_PAD src0_sel:WORD_1 src1_sel:DWORD
	v_add3_u32 v17, v24, v17, s91
	v_add3_u32 v16, v25, v16, s91
	v_mfma_f32_32x32x16_bf16 v[32:47], v[92:95], v[0:3], 0
	v_and_b32_sdwa v0, v27, v87 dst_sel:DWORD dst_unused:UNUSED_PAD src0_sel:WORD_1 src1_sel:DWORD
	v_and_b32_sdwa v1, v26, v87 dst_sel:DWORD dst_unused:UNUSED_PAD src0_sel:WORD_1 src1_sel:DWORD
	v_add3_u32 v1, v26, v1, s91
	v_add3_u32 v0, v27, v0, s91
	v_perm_b32 v1, v0, v1, s93
	v_perm_b32 v0, v16, v17, s93
	global_store_dwordx2 v[70:71], v[0:1], off offset:32
	v_and_b32_sdwa v0, v9, v87 dst_sel:DWORD dst_unused:UNUSED_PAD src0_sel:WORD_1 src1_sel:DWORD
	v_and_b32_sdwa v1, v8, v87 dst_sel:DWORD dst_unused:UNUSED_PAD src0_sel:WORD_1 src1_sel:DWORD
	v_add3_u32 v8, v8, v1, s91
	v_add3_u32 v9, v9, v0, s91
	ds_read_b128 v[0:3], v69 offset:22080
	s_waitcnt lgkmcnt(1)
	v_mfma_f32_32x32x16_bf16 v[48:63], v[4:7], v[88:91], v[48:63]
	v_and_b32_sdwa v16, v11, v87 dst_sel:DWORD dst_unused:UNUSED_PAD src0_sel:WORD_1 src1_sel:DWORD
	v_and_b32_sdwa v17, v10, v87 dst_sel:DWORD dst_unused:UNUSED_PAD src0_sel:WORD_1 src1_sel:DWORD
	v_mfma_f32_32x32x16_bf16 v[32:47], v[96:99], v[4:7], v[32:47]
	v_add3_u32 v4, v10, v17, s91
	v_add3_u32 v5, v11, v16, s91
	v_perm_b32 v5, v5, v4, s93
	v_perm_b32 v4, v9, v8, s93
	global_store_dwordx2 v[118:119], v[4:5], off offset:32
	ds_read_b128 v[4:7], v69 offset:22112
	v_and_b32_sdwa v8, v29, v87 dst_sel:DWORD dst_unused:UNUSED_PAD src0_sel:WORD_1 src1_sel:DWORD
	s_waitcnt lgkmcnt(1)
	v_mfma_f32_32x32x16_bf16 v[48:63], v[0:3], v[100:103], v[48:63]
	v_and_b32_sdwa v9, v28, v87 dst_sel:DWORD dst_unused:UNUSED_PAD src0_sel:WORD_1 src1_sel:DWORD
	v_and_b32_sdwa v10, v31, v87 dst_sel:DWORD dst_unused:UNUSED_PAD src0_sel:WORD_1 src1_sel:DWORD
	v_and_b32_sdwa v11, v30, v87 dst_sel:DWORD dst_unused:UNUSED_PAD src0_sel:WORD_1 src1_sel:DWORD
	v_add3_u32 v9, v28, v9, s91
	v_add3_u32 v8, v29, v8, s91
	v_add3_u32 v11, v30, v11, s91
	v_add3_u32 v10, v31, v10, s91
	v_mfma_f32_32x32x16_bf16 v[32:47], v[108:111], v[0:3], v[32:47]
	v_perm_b32 v1, v10, v11, s93
	v_perm_b32 v0, v8, v9, s93
	global_store_dwordx2 v[70:71], v[0:1], off offset:48
	v_and_b32_sdwa v1, v12, v87 dst_sel:DWORD dst_unused:UNUSED_PAD src0_sel:WORD_1 src1_sel:DWORD
	v_add3_u32 v2, v12, v1, s91
	v_and_b32_sdwa v1, v15, v87 dst_sel:DWORD dst_unused:UNUSED_PAD src0_sel:WORD_1 src1_sel:DWORD
	v_and_b32_sdwa v3, v14, v87 dst_sel:DWORD dst_unused:UNUSED_PAD src0_sel:WORD_1 src1_sel:DWORD
	s_waitcnt lgkmcnt(0)
	v_mfma_f32_32x32x16_bf16 v[48:63], v[4:7], v[104:107], v[48:63]
	v_and_b32_sdwa v0, v13, v87 dst_sel:DWORD dst_unused:UNUSED_PAD src0_sel:WORD_1 src1_sel:DWORD
	v_add3_u32 v3, v14, v3, s91
	v_add3_u32 v1, v15, v1, s91
	v_add3_u32 v0, v13, v0, s91
	v_perm_b32 v1, v1, v3, s93
	v_perm_b32 v0, v0, v2, s93
	global_store_dwordx2 v[118:119], v[0:1], off offset:48
	v_mfma_f32_32x32x16_bf16 v[32:47], v[112:115], v[4:7], v[32:47]
	s_nop 3
	v_and_b32_sdwa v3, v48, v87 dst_sel:DWORD dst_unused:UNUSED_PAD src0_sel:WORD_1 src1_sel:DWORD
	v_and_b32_sdwa v2, v49, v87 dst_sel:DWORD dst_unused:UNUSED_PAD src0_sel:WORD_1 src1_sel:DWORD
	v_add3_u32 v4, v48, v3, s91
	v_and_b32_sdwa v3, v51, v87 dst_sel:DWORD dst_unused:UNUSED_PAD src0_sel:WORD_1 src1_sel:DWORD
	v_and_b32_sdwa v5, v50, v87 dst_sel:DWORD dst_unused:UNUSED_PAD src0_sel:WORD_1 src1_sel:DWORD
	v_add3_u32 v2, v49, v2, s91
	v_add3_u32 v5, v50, v5, s91
	v_add3_u32 v3, v51, v3, s91
	v_perm_b32 v3, v3, v5, s93
	v_perm_b32 v2, v2, v4, s93
	global_store_dwordx2 v[70:71], v[2:3], off offset:64
	v_and_b32_sdwa v3, v32, v87 dst_sel:DWORD dst_unused:UNUSED_PAD src0_sel:WORD_1 src1_sel:DWORD
	v_and_b32_sdwa v2, v33, v87 dst_sel:DWORD dst_unused:UNUSED_PAD src0_sel:WORD_1 src1_sel:DWORD
	v_add3_u32 v4, v32, v3, s91
	v_and_b32_sdwa v3, v35, v87 dst_sel:DWORD dst_unused:UNUSED_PAD src0_sel:WORD_1 src1_sel:DWORD
	v_and_b32_sdwa v5, v34, v87 dst_sel:DWORD dst_unused:UNUSED_PAD src0_sel:WORD_1 src1_sel:DWORD
	v_add3_u32 v2, v33, v2, s91
	v_add3_u32 v5, v34, v5, s91
	v_add3_u32 v3, v35, v3, s91
	v_lshl_add_u64 v[0:1], v[116:117], 0, v[64:65]
	v_perm_b32 v3, v3, v5, s93
	v_perm_b32 v2, v2, v4, s93
	global_store_dwordx2 v[0:1], v[2:3], off
	v_and_b32_sdwa v3, v52, v87 dst_sel:DWORD dst_unused:UNUSED_PAD src0_sel:WORD_1 src1_sel:DWORD
	v_and_b32_sdwa v2, v53, v87 dst_sel:DWORD dst_unused:UNUSED_PAD src0_sel:WORD_1 src1_sel:DWORD
	v_add3_u32 v4, v52, v3, s91
	v_and_b32_sdwa v3, v55, v87 dst_sel:DWORD dst_unused:UNUSED_PAD src0_sel:WORD_1 src1_sel:DWORD
	v_and_b32_sdwa v5, v54, v87 dst_sel:DWORD dst_unused:UNUSED_PAD src0_sel:WORD_1 src1_sel:DWORD
	v_add3_u32 v2, v53, v2, s91
	v_add3_u32 v5, v54, v5, s91
	v_add3_u32 v3, v55, v3, s91
	v_perm_b32 v3, v3, v5, s93
	v_perm_b32 v2, v2, v4, s93
	global_store_dwordx2 v[70:71], v[2:3], off offset:80
	v_and_b32_sdwa v3, v36, v87 dst_sel:DWORD dst_unused:UNUSED_PAD src0_sel:WORD_1 src1_sel:DWORD
	v_and_b32_sdwa v2, v37, v87 dst_sel:DWORD dst_unused:UNUSED_PAD src0_sel:WORD_1 src1_sel:DWORD
	v_add3_u32 v4, v36, v3, s91
	v_and_b32_sdwa v3, v39, v87 dst_sel:DWORD dst_unused:UNUSED_PAD src0_sel:WORD_1 src1_sel:DWORD
	v_and_b32_sdwa v5, v38, v87 dst_sel:DWORD dst_unused:UNUSED_PAD src0_sel:WORD_1 src1_sel:DWORD
	v_add3_u32 v2, v37, v2, s91
	v_add3_u32 v5, v38, v5, s91
	v_add3_u32 v3, v39, v3, s91
	v_perm_b32 v3, v3, v5, s93
	v_perm_b32 v2, v2, v4, s93
	global_store_dwordx2 v[0:1], v[2:3], off offset:16
	v_and_b32_sdwa v3, v56, v87 dst_sel:DWORD dst_unused:UNUSED_PAD src0_sel:WORD_1 src1_sel:DWORD
	v_and_b32_sdwa v2, v57, v87 dst_sel:DWORD dst_unused:UNUSED_PAD src0_sel:WORD_1 src1_sel:DWORD
	v_add3_u32 v4, v56, v3, s91
	v_and_b32_sdwa v3, v59, v87 dst_sel:DWORD dst_unused:UNUSED_PAD src0_sel:WORD_1 src1_sel:DWORD
	v_and_b32_sdwa v5, v58, v87 dst_sel:DWORD dst_unused:UNUSED_PAD src0_sel:WORD_1 src1_sel:DWORD
	v_add3_u32 v2, v57, v2, s91
	v_add3_u32 v5, v58, v5, s91
	v_add3_u32 v3, v59, v3, s91
	v_perm_b32 v3, v3, v5, s93
	v_perm_b32 v2, v2, v4, s93
	global_store_dwordx2 v[70:71], v[2:3], off offset:96
	v_and_b32_sdwa v3, v40, v87 dst_sel:DWORD dst_unused:UNUSED_PAD src0_sel:WORD_1 src1_sel:DWORD
	v_and_b32_sdwa v2, v41, v87 dst_sel:DWORD dst_unused:UNUSED_PAD src0_sel:WORD_1 src1_sel:DWORD
	v_add3_u32 v4, v40, v3, s91
	v_and_b32_sdwa v3, v43, v87 dst_sel:DWORD dst_unused:UNUSED_PAD src0_sel:WORD_1 src1_sel:DWORD
	v_and_b32_sdwa v5, v42, v87 dst_sel:DWORD dst_unused:UNUSED_PAD src0_sel:WORD_1 src1_sel:DWORD
	v_add3_u32 v2, v41, v2, s91
	v_add3_u32 v5, v42, v5, s91
	v_add3_u32 v3, v43, v3, s91
	v_perm_b32 v3, v3, v5, s93
	v_perm_b32 v2, v2, v4, s93
	global_store_dwordx2 v[0:1], v[2:3], off offset:32
	v_and_b32_sdwa v3, v60, v87 dst_sel:DWORD dst_unused:UNUSED_PAD src0_sel:WORD_1 src1_sel:DWORD
	v_and_b32_sdwa v2, v61, v87 dst_sel:DWORD dst_unused:UNUSED_PAD src0_sel:WORD_1 src1_sel:DWORD
	v_add3_u32 v4, v60, v3, s91
	v_and_b32_sdwa v3, v63, v87 dst_sel:DWORD dst_unused:UNUSED_PAD src0_sel:WORD_1 src1_sel:DWORD
	v_and_b32_sdwa v5, v62, v87 dst_sel:DWORD dst_unused:UNUSED_PAD src0_sel:WORD_1 src1_sel:DWORD
	v_add3_u32 v2, v61, v2, s91
	v_add3_u32 v5, v62, v5, s91
	v_add3_u32 v3, v63, v3, s91
	v_perm_b32 v3, v3, v5, s93
	v_perm_b32 v2, v2, v4, s93
	global_store_dwordx2 v[70:71], v[2:3], off offset:112
	v_and_b32_sdwa v3, v44, v87 dst_sel:DWORD dst_unused:UNUSED_PAD src0_sel:WORD_1 src1_sel:DWORD
	v_and_b32_sdwa v2, v45, v87 dst_sel:DWORD dst_unused:UNUSED_PAD src0_sel:WORD_1 src1_sel:DWORD
	v_add3_u32 v4, v44, v3, s91
	v_and_b32_sdwa v3, v47, v87 dst_sel:DWORD dst_unused:UNUSED_PAD src0_sel:WORD_1 src1_sel:DWORD
	v_and_b32_sdwa v5, v46, v87 dst_sel:DWORD dst_unused:UNUSED_PAD src0_sel:WORD_1 src1_sel:DWORD
	v_add3_u32 v2, v45, v2, s91
	v_add3_u32 v5, v46, v5, s91
	v_add3_u32 v3, v47, v3, s91
	v_perm_b32 v3, v3, v5, s93
	v_perm_b32 v2, v2, v4, s93
	global_store_dwordx2 v[0:1], v[2:3], off offset:48
	s_barrier
	s_cbranch_scc1 .LBB0_285

.LBB0_285:
	s_cmp_lg_u32 s98, 1
	s_cbranch_scc1 .Lrr_a
	s_nop 0
	v_writelane_b32 v250, s99, 9
	s_nop 1

.LBB0_296:
	s_or_b64 exec, exec, s[2:3]
	s_cmp_lg_u32 s98, 1
	s_cbranch_scc1 .Lrr_b
	s_mov_b32 s98, 2
	s_waitcnt vmcnt(0)
	buffer_wbl2 sc1
	s_waitcnt vmcnt(0)
	s_barrier
	v_readlane_b32 s0, v252, 0
	v_readlane_b32 s1, v252, 1
	s_add_u32 s0, s0, 0x12a8100
	s_addc_u32 s1, s1, 0
	v_mov_b32_e32 v0, 0
	v_mov_b32_e32 v1, 1
	v_cmp_eq_u32_e32 vcc, 0, v218
	s_nop 1
	s_and_saveexec_b64 s[2:3], vcc
	global_atomic_add v0, v1, s[0:1]
	s_mov_b64 exec, s[2:3]
	s_waitcnt vmcnt(0)
	s_mov_b64 s[0:1], exec
	s_branch .LBB0_361

.LBB0_361:
	s_or_b64 exec, exec, s[0:1]
	s_cmp_lg_u32 s98, 0
	s_cbranch_scc1 .Lrr_cont
	v_readlane_b32 s0, v250, 9
	s_sub_i32 s1, s0, 192
	s_cmp_lt_u32 s1, 8
	s_cbranch_scc0 .Lrr_cont
	s_mov_b32 s98, 1
	s_mov_b32 s99, s0
	s_add_i32 s78, s1, 0x400
	s_branch .LBB0_203
.Lrr_cont:
	v_readlane_b32 s2, v252, 0
	v_readlane_b32 s3, v252, 1
	s_add_u32 s0, s2, 0x880000
	s_addc_u32 s1, s3, 0
	v_writelane_b32 v250, s0, 13
	v_readlane_b32 s4, v252, 2
	s_waitcnt lgkmcnt(0)
	v_writelane_b32 v250, s1, 14
	s_add_u32 s0, s2, 0xe80000
	s_addc_u32 s1, s3, 0
	v_writelane_b32 v250, s0, 15
	s_barrier
	s_nop 0
	v_writelane_b32 v250, s1, 16
	s_add_u32 s0, s2, 0x7c4b700
	s_addc_u32 s1, s3, 0
	v_writelane_b32 v250, s0, 17
	v_readlane_b32 s5, v252, 3
	s_nop 0
	v_writelane_b32 v250, s1, 18
	s_not_b32 s0, s94
	s_add_i32 s0, s4, s0
	s_add_u32 s76, s2, 0x7c4bb00
	s_addc_u32 s77, s3, 0
	v_writelane_b32 v250, s0, 19
	s_cmp_gt_i32 s94, 31
	s_mov_b64 s[0:1], -1
	s_cbranch_scc0 .LBB0_475
	v_readlane_b32 s0, v252, 2
	s_sub_i32 s91, s94, 0x100
	s_cmp_lt_u32 s91, 32
	s_cbranch_scc1 .LBB0_474
	s_sub_i32 s91, s0, 64
	s_cmpk_gt_u32 s94, 0xff
	s_cselect_b32 s1, 64, 32
	s_sub_i32 s92, s94, s1
	v_writelane_b32 v250, s31, 20
	s_cmpk_gt_u32 s92, 0x40f
	v_writelane_b32 v250, s30, 22
	v_readlane_b32 s1, v252, 3
	s_cbranch_scc1 .LBB0_367
	v_readlane_b32 s0, v252, 37
	v_mbcnt_hi_u32_b32 v165, -1, v219
	v_readlane_b32 s1, v252, 38
	v_and_b32_e32 v0, 64, v165
	v_mov_b32_e32 v156, 0x200f
	s_movk_i32 s17, 0x1a00
	v_mov_b64_e32 v[146:147], s[0:1]
	s_mov_b32 s3, 0
	v_mov_b32_e32 v149, 0
	s_movk_i32 s33, 0x80
	s_mov_b32 s16, 0x3e000000
	v_mov_b32_e32 v157, 0xf149f2ca
	v_not_b32_e32 v158, 16
	v_not_b32_e32 v159, 17
	v_not_b32_e32 v160, 18
	v_not_b32_e32 v161, 23
	v_not_b32_e32 v162, 24
	v_not_b32_e32 v163, 25
	v_not_b32_e32 v164, 26
	v_xor_b32_e32 v166, 32, v165
	v_add_u32_e32 v167, 64, v0
	s_mov_b32 s38, 0xefa18f08
	s_mov_b64 s[18:19], 0x106000
	s_mov_b32 s39, 0x106000
	s_movk_i32 s40, 0x7fff
	s_mov_b32 s41, 0x7060302
	v_mov_b32_e32 v168, 1
	s_mov_b32 s42, s92
	s_branch .LBB0_365

.LBB0_478:
	s_cmp_lg_u32 s8, 0x200000
	s_cbranch_scc1 .Ldnl1_go
	s_add_u32 s4, s98, 0x12a8100
	s_addc_u32 s5, s99, 0
	s_mov_b32 s21, 0
.Ldnl1_spin:
	global_load_dword v16, v157, s[4:5] sc1
	s_waitcnt vmcnt(0)
	v_readfirstlane_b32 s20, v16
	s_cmp_ge_u32 s20, 8
	s_cbranch_scc1 .Ldnl1_acq
	s_sleep 4
	s_add_i32 s21, s21, 1
	s_cmp_lt_u32 s21, 0x2000
	s_cbranch_scc1 .Ldnl1_spin
.Ldnl1_acq:
	buffer_inv sc1
.Ldnl1_go:
	v_lshl_add_u64 v[16:17], v[168:169], 0, s[8:9]
	s_mov_b32 s4, 0x7489000
	v_add_co_u32_e64 v18, s[4:5], s4, v16
	v_add_u32_e32 v179, 0xe800, v174
	s_nop 0
	v_addc_co_u32_e64 v19, s[4:5], 0, v17, s[4:5]
	s_mov_b32 s4, 0x748a000
	s_nop 0
	v_add_co_u32_e64 v20, s[4:5], s4, v16
	s_nop 1
	v_addc_co_u32_e64 v21, s[4:5], 0, v17, s[4:5]
	s_mov_b32 s4, 0x748b000
	global_store_dword v[20:21], v0, off offset:-4096 nt
	global_store_dword v[18:19], v1, off offset:512 nt
	global_store_dword v[18:19], v2, off offset:1024 nt
	global_store_dword v[18:19], v3, off offset:1536 nt
	global_store_dword v[20:21], v4, off nt
	global_store_dword v[20:21], v5, off offset:512 nt
	global_store_dword v[20:21], v6, off offset:1024 nt
	global_store_dword v[20:21], v7, off offset:1536 nt
	v_add_co_u32_e64 v18, s[4:5], s4, v16
	s_nop 0
	v_addc_co_u32_e64 v19, s[4:5], 0, v17, s[4:5]
	s_mov_b32 s4, 0x748c000
	s_nop 0
	v_add_co_u32_e64 v16, s[4:5], s4, v16
	s_nop 0
	v_addc_co_u32_e64 v17, s[4:5], 0, v17, s[4:5]
	global_store_dword v[16:17], v8, off offset:-4096 nt
	global_store_dword v[18:19], v9, off offset:512 nt
	global_store_dword v[18:19], v10, off offset:1024 nt
	global_store_dword v[18:19], v11, off offset:1536 nt
	global_store_dword v[16:17], v12, off nt
	global_store_dword v[16:17], v13, off offset:512 nt
	global_store_dword v[16:17], v14, off offset:1024 nt
	global_store_dword v[16:17], v15, off offset:1536 nt
	v_cvt_pk_bf16_f32 v16, v0, v1
	v_cvt_pk_bf16_f32 v17, v2, v3
	v_cvt_pk_bf16_f32 v18, v4, v5
	v_cvt_pk_bf16_f32 v19, v6, v7
	ds_write2_b64 v159, v[16:17], v[18:19] offset1:2
	v_cvt_pk_bf16_f32 v16, v8, v9
	v_cvt_pk_bf16_f32 v17, v10, v11
	v_cvt_pk_bf16_f32 v18, v12, v13
	v_cvt_pk_bf16_f32 v19, v14, v15
	ds_write2_b64 v159, v[16:17], v[18:19] offset0:4 offset1:6
	s_waitcnt lgkmcnt(0)
	s_barrier
	ds_read_b128 v[44:47], v161 offset:41984
	ds_read_b128 v[40:43], v161 offset:42016
	ds_read_b128 v[36:39], v161 offset:42048
	ds_read_b128 v[32:35], v161 offset:42080
	s_and_saveexec_b64 s[4:5], vcc
	s_cbranch_execz .LBB0_480
	ds_read2_b64 v[52:55], v179 offset0:128 offset1:130
	ds_read2_b64 v[48:51], v179 offset0:132 offset1:134

.LBB0_779:
	s_or_b64 exec, exec, s[0:1]
	v_readlane_b32 s2, v250, 9
	s_and_b32 s2, s2, 7
	s_lshl_b32 s2, s2, 4
	s_movk_i32 s3, 0x80
	s_mov_b32 s4, 16
	v_writelane_b32 v252, s2, 40
	v_writelane_b32 v252, s3, 41
	v_writelane_b32 v252, s4, 44
	s_nop 1
	v_readlane_b32 s0, v252, 42
	v_readlane_b32 s17, v252, 41
	v_readlane_b32 s1, v252, 43
	s_cmp_lt_i32 s0, s17
	s_mov_b32 s16, s0
	s_cselect_b64 s[0:1], -1, 0
	v_writelane_b32 v250, s0, 32
	s_waitcnt lgkmcnt(0)
	s_barrier
	v_writelane_b32 v250, s1, 33
	v_readlane_b32 s0, v252, 13
	v_readlane_b32 s14, v252, 27
	v_readlane_b32 s1, v252, 14
	v_readlane_b32 s15, v252, 28
	s_add_u32 s96, s14, 0x4000000
	s_addc_u32 s97, s15, 0
	v_readlane_b32 s0, v252, 0
	v_readlane_b32 s1, v252, 1
	s_add_u32 s0, s0, 0x1206000
	s_addc_u32 s1, s1, 0
	v_writelane_b32 v250, s0, 3
	s_cmp_ge_i32 s16, s17
	v_readlane_b32 s2, v252, 15
	v_readlane_b32 s3, v252, 16
	v_readlane_b32 s4, v252, 17
	v_readlane_b32 s5, v252, 18
	v_readlane_b32 s6, v252, 19
	v_readlane_b32 s7, v252, 20
	v_readlane_b32 s8, v252, 21
	v_readlane_b32 s9, v252, 22
	v_readlane_b32 s10, v252, 23
	v_readlane_b32 s11, v252, 24
	v_readlane_b32 s12, v252, 25
	v_readlane_b32 s13, v252, 26
	v_writelane_b32 v250, s1, 4
	s_cbranch_scc1 .LBB0_1679
	v_readlane_b32 s0, v252, 41
	s_abs_i32 s1, s0
	v_cvt_f32_u32_e32 v0, s1
	v_writelane_b32 v250, s59, 34
	v_writelane_b32 v250, s58, 35
	s_ashr_i32 s0, s0, 31
	v_rcp_iflag_f32_e32 v0, v0
	v_writelane_b32 v250, s0, 36
	v_readlane_b32 s0, v252, 44
	s_sub_i32 s0, 0, s0
	v_mul_f32_e32 v0, 0x4f7ffffe, v0
	v_cvt_u32_f32_e32 v0, v0
	v_writelane_b32 v250, s0, 37
	v_writelane_b32 v250, s1, 38
	s_sub_i32 s0, 0, s1
	v_readfirstlane_b32 s1, v0
	s_mul_i32 s0, s0, s1
	s_mul_hi_u32 s0, s1, s0
	s_add_i32 s0, s1, s0
	v_writelane_b32 v250, s0, 39
	v_readlane_b32 s0, v252, 42
	v_mov_b32_e32 v65, 0
	s_movk_i32 s33, 0x401f
	s_movk_i32 s88, 0x2010
	v_mov_b32_e32 v171, 0xffffdff0
	s_movk_i32 s89, 0x200f
	s_movk_i32 s92, 0x40a0
	v_mov_b32_e32 v172, 0x1ff0
	s_mov_b32 s93, s0
	v_readlane_b32 s1, v252, 43
	s_branch .LBB0_782

.LBB0_1679:
	s_barrier
	v_readlane_b32 s2, v250, 9
	s_cmpk_gt_u32 s2, 0x9f
	s_cbranch_scc1 .Ltail1_end
	s_lshr_b32 s3, s2, 5
	s_and_b32 s4, s2, 31
	v_readlane_b32 s8, v250, 17
	v_readlane_b32 s9, v250, 18
	s_lshl_b32 s5, s3, 16
	s_add_i32 s5, s5, 0x2000000
	s_add_u32 s8, s8, s5
	s_addc_u32 s9, s9, 0
	v_readlane_b32 s10, v252, 6
	v_readlane_b32 s11, v252, 7
	s_lshl_b32 s5, s4, 16
	s_add_u32 s10, s10, s5
	s_addc_u32 s11, s11, 0
	v_and_b32_e32 v66, 31, v218
	v_lshrrev_b32_e32 v77, 6, v218
	v_bfe_u32 v78, v218, 5, 1
	v_lshlrev_b32_e32 v79, 2, v66
	v_lshlrev_b32_e32 v66, 11, v66
	v_lshl_add_u32 v66, v77, 9, v66
	v_lshl_add_u32 v66, v78, 4, v66
	global_load_dwordx4 v[82:85], v66, s[8:9]
	global_load_dwordx4 v[16:19], v66, s[10:11]
	global_load_dwordx4 v[86:89], v66, s[8:9] offset:32
	global_load_dwordx4 v[20:23], v66, s[10:11] offset:32
	global_load_dwordx4 v[90:93], v66, s[8:9] offset:64
	global_load_dwordx4 v[24:27], v66, s[10:11] offset:64
	global_load_dwordx4 v[94:97], v66, s[8:9] offset:96
	global_load_dwordx4 v[28:31], v66, s[10:11] offset:96
	global_load_dwordx4 v[98:101], v66, s[8:9] offset:128
	global_load_dwordx4 v[32:35], v66, s[10:11] offset:128
	global_load_dwordx4 v[102:105], v66, s[8:9] offset:160
	global_load_dwordx4 v[36:39], v66, s[10:11] offset:160
	global_load_dwordx4 v[106:109], v66, s[8:9] offset:192
	global_load_dwordx4 v[40:43], v66, s[10:11] offset:192
	global_load_dwordx4 v[110:113], v66, s[8:9] offset:224
	global_load_dwordx4 v[44:47], v66, s[10:11] offset:224
	global_load_dwordx4 v[114:117], v66, s[8:9] offset:256
	global_load_dwordx4 v[48:51], v66, s[10:11] offset:256
	global_load_dwordx4 v[118:121], v66, s[8:9] offset:288
	global_load_dwordx4 v[52:55], v66, s[10:11] offset:288
	global_load_dwordx4 v[122:125], v66, s[8:9] offset:320
	global_load_dwordx4 v[56:59], v66, s[10:11] offset:320
	global_load_dwordx4 v[126:129], v66, s[8:9] offset:352
	global_load_dwordx4 v[60:63], v66, s[10:11] offset:352
	global_load_dwordx4 v[130:133], v66, s[8:9] offset:384
	global_load_dwordx4 v[150:153], v66, s[10:11] offset:384
	global_load_dwordx4 v[136:139], v66, s[8:9] offset:416
	global_load_dwordx4 v[154:157], v66, s[10:11] offset:416
	global_load_dwordx4 v[140:143], v66, s[8:9] offset:448
	global_load_dwordx4 v[158:161], v66, s[10:11] offset:448
	global_load_dwordx4 v[144:147], v66, s[8:9] offset:480
	global_load_dwordx4 v[162:165], v66, s[10:11] offset:480
	v_readlane_b32 s12, v252, 27
	v_readlane_b32 s13, v252, 28
	s_cmp_eq_u32 s3, 0
	s_cbranch_scc1 .Ltail1_p
	s_add_i32 s5, s3, -1
	s_lshl_b32 s5, s5, 17
	s_add_u32 s14, s62, s5
	s_addc_u32 s15, s63, 0
	s_add_u32 s16, s96, s5
	s_addc_u32 s17, s97, 0
	s_branch .Ltail1_q
.Ltail1_p:
	s_add_u32 s14, s60, 0x3fe0000
	s_addc_u32 s15, s61, 0
	s_add_u32 s16, s12, 0x3fe0000
	s_addc_u32 s17, s13, 0
.Ltail1_q:
	s_lshl_b32 s5, s4, 7
	s_add_u32 s14, s14, s5
	s_addc_u32 s15, s15, 0
	s_add_u32 s16, s16, s5
	s_addc_u32 s17, s17, 0
	v_lshl_add_u32 v67, v77, 15, v79
	v_lshl_add_u32 v67, v78, 14, v67
	v_add_u32_e32 v68, 0x1000, v67
	v_add_u32_e32 v69, 0x2000, v67
	v_add_u32_e32 v70, 0x3000, v67
	global_load_dword v71, v67, s[14:15] nt
	global_load_dword v72, v68, s[14:15] nt
	global_load_dword v73, v69, s[14:15] nt
	global_load_dword v74, v70, s[14:15] nt
	v_and_b32_e32 v75, 63, v218
	v_lshlrev_b32_e32 v75, 4, v75
	v_lshl_add_u32 v76, v77, 10, v75
	v_lshl_add_u32 v75, v77, 12, v75
	s_waitcnt vmcnt(34)
	v_mfma_f32_32x32x16_bf16 v[0:15], v[82:85], v[16:19], 0
	s_waitcnt vmcnt(32)
	v_mfma_f32_32x32x16_bf16 v[0:15], v[86:89], v[20:23], v[0:15]
	s_waitcnt vmcnt(30)
	v_mfma_f32_32x32x16_bf16 v[0:15], v[90:93], v[24:27], v[0:15]
	s_waitcnt vmcnt(28)
	v_mfma_f32_32x32x16_bf16 v[0:15], v[94:97], v[28:31], v[0:15]
	s_waitcnt vmcnt(26)
	v_mfma_f32_32x32x16_bf16 v[0:15], v[98:101], v[32:35], v[0:15]
	s_waitcnt vmcnt(24)
	v_mfma_f32_32x32x16_bf16 v[0:15], v[102:105], v[36:39], v[0:15]
	s_waitcnt vmcnt(22)
	v_mfma_f32_32x32x16_bf16 v[0:15], v[106:109], v[40:43], v[0:15]
	s_waitcnt vmcnt(20)
	v_mfma_f32_32x32x16_bf16 v[0:15], v[110:113], v[44:47], v[0:15]
	s_waitcnt vmcnt(18)
	v_mfma_f32_32x32x16_bf16 v[0:15], v[114:117], v[48:51], v[0:15]
	s_waitcnt vmcnt(16)
	v_mfma_f32_32x32x16_bf16 v[0:15], v[118:121], v[52:55], v[0:15]
	s_waitcnt vmcnt(14)
	v_mfma_f32_32x32x16_bf16 v[0:15], v[122:125], v[56:59], v[0:15]
	s_waitcnt vmcnt(12)
	v_mfma_f32_32x32x16_bf16 v[0:15], v[126:129], v[60:63], v[0:15]
	s_waitcnt vmcnt(10)
	v_mfma_f32_32x32x16_bf16 v[0:15], v[130:133], v[150:153], v[0:15]
	s_waitcnt vmcnt(8)
	v_mfma_f32_32x32x16_bf16 v[0:15], v[136:139], v[154:157], v[0:15]
	s_waitcnt vmcnt(6)
	v_mfma_f32_32x32x16_bf16 v[0:15], v[140:143], v[158:161], v[0:15]
	s_waitcnt vmcnt(4)
	v_mfma_f32_32x32x16_bf16 v[0:15], v[144:147], v[162:165], v[0:15]
	s_nop 15
	s_nop 15
	ds_write_b128 v75, v[0:3]
	ds_write_b128 v75, v[4:7] offset:1024
	ds_write_b128 v75, v[8:11] offset:2048
	ds_write_b128 v75, v[12:15] offset:3072
	s_waitcnt lgkmcnt(0)
	s_barrier
	ds_read_b128 v[16:19], v76
	ds_read_b128 v[20:23], v76 offset:4096
	ds_read_b128 v[24:27], v76 offset:8192
	ds_read_b128 v[28:31], v76 offset:12288
	s_waitcnt lgkmcnt(0)
	v_pk_add_f32 v[16:17], v[16:17], v[20:21]
	v_pk_add_f32 v[18:19], v[18:19], v[22:23]
	v_pk_add_f32 v[24:25], v[24:25], v[28:29]
	v_pk_add_f32 v[26:27], v[26:27], v[30:31]
	v_pk_add_f32 v[16:17], v[16:17], v[24:25]
	v_pk_add_f32 v[18:19], v[18:19], v[26:27]
	s_waitcnt vmcnt(0)
	v_add_f32_e32 v71, v71, v16
	global_store_dword v67, v71, s[16:17]
	v_add_f32_e32 v72, v72, v17
	global_store_dword v68, v72, s[16:17]
	v_add_f32_e32 v73, v73, v18
	global_store_dword v69, v73, s[16:17]
	v_add_f32_e32 v74, v74, v19
	global_store_dword v70, v74, s[16:17]
.Ltail1_end:
	v_readlane_b32 s2, v250, 9
	s_and_b32 s2, s2, 7
	s_mul_i32 s3, s2, 0x82
	s_lshr_b32 s4, s3, 3
	s_addk_i32 s3, 0x82
	s_lshr_b32 s3, s3, 3
	s_sub_i32 s3, s3, s4
	s_lshl_b32 s5, s3, 3
	v_writelane_b32 v252, s4, 40
	v_writelane_b32 v252, s5, 41
	v_writelane_b32 v252, s3, 44
	s_nop 1
	s_waitcnt vmcnt(0)
	v_readlane_b32 s4, v252, 31
	v_readlane_b32 s5, v252, 32
	s_barrier
	s_mov_b64 s[2:3], exec
	v_readlane_b32 s0, v252, 33
	v_readlane_b32 s1, v252, 34
	s_and_b64 s[0:1], s[2:3], s[0:1]
	s_mov_b64 exec, s[0:1]
	s_cbranch_execz .LBB0_1691
	v_mov_b32_e32 v0, 0x12400
	ds_read_b32 v0, v0
	s_mov_b64 s[0:1], -1
	s_waitcnt lgkmcnt(0)
	v_cmp_eq_u32_e32 vcc, 0, v0
	s_cbranch_vccz .LBB0_1690
	s_waitcnt vmcnt(3)
	v_mbcnt_hi_u32_b32 v5, -1, v219
	v_and_b32_e32 v0, 64, v5
	s_waitcnt vmcnt(2)
	v_add_u32_e32 v6, 64, v0
	v_xor_b32_e32 v0, 32, v5
	v_cmp_lt_i32_e32 vcc, v0, v6
	v_xor_b32_e32 v1, 16, v5
	v_xor_b32_e32 v2, 8, v5
	v_cndmask_b32_e32 v0, v5, v0, vcc
	v_cmp_lt_i32_e32 vcc, v1, v6
	v_xor_b32_e32 v3, 4, v5
	v_xor_b32_e32 v4, 2, v5
	v_cndmask_b32_e32 v1, v5, v1, vcc
	v_cmp_lt_i32_e32 vcc, v2, v6
	v_xor_b32_e32 v7, 1, v5
	v_lshlrev_b32_e32 v0, 2, v0
	v_cndmask_b32_e32 v2, v5, v2, vcc
	v_cmp_lt_i32_e32 vcc, v3, v6
	v_lshlrev_b32_e32 v1, 2, v1
	v_lshlrev_b32_e32 v2, 2, v2
	v_cndmask_b32_e32 v3, v5, v3, vcc
	v_cmp_lt_i32_e32 vcc, v4, v6
	v_lshlrev_b32_e32 v3, 2, v3
	s_mov_b64 s[4:5], 0
	v_cndmask_b32_e32 v4, v5, v4, vcc
	v_cmp_lt_i32_e32 vcc, v7, v6
	v_lshlrev_b32_e32 v4, 2, v4
	v_mov_b32_e32 v6, 0x100000
	v_cndmask_b32_e32 v5, v5, v7, vcc
	v_lshlrev_b32_e32 v5, 2, v5
	s_branch .LBB0_1683
